# SEAM 5 hidden inside P6's K-loop: release after the SGU (polled at P6 start), y_r write-through, P5 counter polled at K-tile 10
# speedup vs baseline: 1.0126x; 1.0081x over previous
.LBB0_299:
	s_waitcnt vmcnt(0)
	s_barrier
	s_mov_b64 s[0:1], exec
	v_readlane_b32 s4, v246, 2
	v_readlane_b32 s5, v246, 3
	s_and_b64 s[4:5], s[0:1], s[4:5]
	s_mov_b64 exec, s[4:5]
	s_cbranch_execz .LBB0_308
	v_mov_b32_e32 v2, 0
	s_lshl_b32 s98, s33, 8
	s_add_u32 s98, s98, 0x560c0
	s_add_u32 s98, s92, s98
	s_addc_u32 s99, s93, 0
	v_mov_b32_e32 v3, 1
	global_atomic_add v3, v2, v3, s[98:99] sc0
	v_readlane_b32 s100, v246, 8
	s_waitcnt vmcnt(0)
	v_readfirstlane_b32 s101, v3
	s_add_u32 s101, s101, 1
	s_cmp_lg_u32 s101, s100
	s_cbranch_scc1 .Lsbg_done
	buffer_wbl2 sc1
	s_waitcnt vmcnt(0)
	s_add_u32 s98, s92, 0x57180
	s_addc_u32 s99, s93, 0
	v_mov_b32_e32 v3, s100
	global_atomic_add v2, v3, s[98:99]
.Lsbg_done:
	s_add_u32 s4, s92, 0x3900
	s_addc_u32 s5, s93, 0
	s_mov_b32 s8, 0x400001
	s_waitcnt vmcnt(7)
	v_mov_b32_e32 v2, 0
	s_branch .LBB0_302

.LBB0_556:
	s_cmp_gt_i32 s95, 6
	s_cselect_b64 s[0:1], -1, 0
	s_and_b64 s[4:5], s[58:59], s[0:1]
	s_andn2_b64 vcc, exec, s[4:5]
	s_cbranch_vccnz .LBB0_610
	s_waitcnt vmcnt(0) lgkmcnt(0)
	s_barrier
	s_mov_b64 s[4:5], exec
	v_readlane_b32 s6, v246, 2
	v_readlane_b32 s7, v246, 3
	s_and_b64 s[6:7], s[4:5], s[6:7]
	s_mov_b64 exec, s[6:7]
	s_cbranch_execz .Lsb5_end
	s_add_u32 s8, s92, 0x57100
	s_addc_u32 s9, s93, 0
	v_mov_b32_e32 v2, 0
	v_mov_b32_e32 v3, 1
	global_atomic_add v2, v3, s[8:9]
	buffer_inv sc1
	s_add_u32 s8, s92, 0x57180
	s_addc_u32 s9, s93, 0
	s_mov_b32 s10, 0x400000
	s_movk_i32 s11, 0xff

.LBB0_624:
	s_cmpk_lg_i32 s40, 0x500
	s_cbranch_scc1 .Lk6_go
	s_mov_b64 s[100:101], exec
	v_readlane_b32 s98, v246, 2
	v_readlane_b32 s99, v246, 3
	s_and_b64 s[98:99], s[100:101], s[98:99]
	s_mov_b64 exec, s[98:99]
	s_cbranch_execz .Lk6_chk_end
	s_add_u32 s98, s92, 0x57100
	s_addc_u32 s99, s93, 0
	v_mov_b32_e32 v250, 0
	v_mov_b32_e32 v252, 0x400000
.Lk6_poll:
	global_load_dword v251, v250, s[98:99] sc1
	s_waitcnt vmcnt(0)
	v_cmp_gt_u32_e32 vcc, 0x100, v251
	s_cbranch_vccz .Lk6_chk_end
	s_sleep 1
	v_add_u32_e32 v252, -1, v252
	v_cmp_ne_u32_e32 vcc, 0, v252
	s_cbranch_vccnz .Lk6_poll
.Lk6_chk_end:
	s_mov_b64 exec, s[100:101]
.Lk6_go:
	s_cmpk_lg_i32 s40, 0x800
	s_cbranch_scc1 .LBB0_623
	v_lshlrev_b32_e32 v3, 10, v180
	v_add_lshl_u32 v3, v3, v182, 1
	v_mov_b32_e32 v4, v3
	global_load_dwordx4 v[192:195], v4, s[8:9]
	global_load_dwordx4 v[196:199], v4, s[10:11]
	global_load_dwordx4 v[200:203], v4, s[8:9] offset:256
	global_load_dwordx4 v[204:207], v4, s[10:11] offset:256
	v_add_u32_e32 v4, 0x8000, v3
	global_load_dwordx4 v[208:211], v4, s[8:9]
	global_load_dwordx4 v[212:215], v4, s[10:11]
	global_load_dwordx4 v[216:219], v4, s[8:9] offset:256
	global_load_dwordx4 v[220:223], v4, s[10:11] offset:256
	v_add_u32_e32 v4, 0x10000, v3
	global_load_dwordx4 v[224:227], v4, s[8:9]
	global_load_dwordx4 v[228:231], v4, s[10:11]
	global_load_dwordx4 v[134:137], v4, s[8:9] offset:256
	global_load_dwordx4 v[138:141], v4, s[10:11] offset:256
	v_add_u32_e32 v4, 0x18000, v3
	global_load_dwordx4 v[142:145], v4, s[8:9]
	global_load_dwordx4 v[146:149], v4, s[10:11]
	global_load_dwordx4 v[150:153], v4, s[8:9] offset:256
	global_load_dwordx4 v[154:157], v4, s[10:11] offset:256
	s_waitcnt vmcnt(14)
	v_lshlrev_b32_e32 v248, 16, v196
	v_and_b32_e32 v249, 0xffff0000, v196
	v_lshlrev_b32_e32 v250, 16, v197
	v_and_b32_e32 v251, 0xffff0000, v197
	v_lshlrev_b32_e32 v252, 16, v198
	v_and_b32_e32 v253, 0xffff0000, v198
	v_lshlrev_b32_e32 v254, 16, v199
	v_and_b32_e32 v255, 0xffff0000, v199
	v_lshlrev_b32_e32 v158, 16, v192
	v_and_b32_e32 v159, 0xffff0000, v192
	v_lshlrev_b32_e32 v160, 16, v193
	v_and_b32_e32 v161, 0xffff0000, v193
	v_lshlrev_b32_e32 v162, 16, v194
	v_and_b32_e32 v163, 0xffff0000, v194
	v_lshlrev_b32_e32 v232, 16, v195
	v_and_b32_e32 v233, 0xffff0000, v195
	v_add_u32_e32 v4, 0x40000, v3
	global_load_dwordx4 v[192:195], v4, s[8:9]
	global_load_dwordx4 v[196:199], v4, s[10:11]
	v_max_f32_e32 v248, 0xda24260, v248
	v_max_f32_e32 v249, 0xda24260, v249
	v_max_f32_e32 v250, 0xda24260, v250
	v_max_f32_e32 v251, 0xda24260, v251
	v_max_f32_e32 v252, 0xda24260, v252
	v_max_f32_e32 v253, 0xda24260, v253
	v_max_f32_e32 v254, 0xda24260, v254
	v_max_f32_e32 v255, 0xda24260, v255
	v_rcp_f32_e32 v248, v248
	v_rcp_f32_e32 v249, v249
	v_rcp_f32_e32 v250, v250
	v_rcp_f32_e32 v251, v251
	v_rcp_f32_e32 v252, v252
	v_rcp_f32_e32 v253, v253
	v_rcp_f32_e32 v254, v254
	v_rcp_f32_e32 v255, v255
	s_nop 0
	v_pk_mul_f32 v[158:159], v[248:249], v[158:159]
	v_pk_mul_f32 v[160:161], v[250:251], v[160:161]
	v_pk_mul_f32 v[162:163], v[252:253], v[162:163]
	v_pk_mul_f32 v[232:233], v[254:255], v[232:233]
	v_pk_mul_f32 v[130:131], v[130:131], v[158:159]
	v_pk_mul_f32 v[132:133], v[132:133], v[160:161]
	v_pk_mul_f32 v[126:127], v[126:127], v[162:163]
	v_pk_mul_f32 v[128:129], v[128:129], v[232:233]
	s_waitcnt vmcnt(14)
	v_lshlrev_b32_e32 v248, 16, v204
	v_and_b32_e32 v249, 0xffff0000, v204
	v_lshlrev_b32_e32 v250, 16, v205
	v_and_b32_e32 v251, 0xffff0000, v205
	v_lshlrev_b32_e32 v252, 16, v206
	v_and_b32_e32 v253, 0xffff0000, v206
	v_lshlrev_b32_e32 v254, 16, v207
	v_and_b32_e32 v255, 0xffff0000, v207
	v_lshlrev_b32_e32 v158, 16, v200
	v_and_b32_e32 v159, 0xffff0000, v200
	v_lshlrev_b32_e32 v160, 16, v201
	v_and_b32_e32 v161, 0xffff0000, v201
	v_lshlrev_b32_e32 v162, 16, v202
	v_and_b32_e32 v163, 0xffff0000, v202
	v_lshlrev_b32_e32 v232, 16, v203
	v_and_b32_e32 v233, 0xffff0000, v203
	global_load_dwordx4 v[200:203], v4, s[8:9] offset:256
	global_load_dwordx4 v[204:207], v4, s[10:11] offset:256
	v_max_f32_e32 v248, 0xda24260, v248
	v_max_f32_e32 v249, 0xda24260, v249
	v_max_f32_e32 v250, 0xda24260, v250
	v_max_f32_e32 v251, 0xda24260, v251
	v_max_f32_e32 v252, 0xda24260, v252
	v_max_f32_e32 v253, 0xda24260, v253
	v_max_f32_e32 v254, 0xda24260, v254
	v_max_f32_e32 v255, 0xda24260, v255
	v_rcp_f32_e32 v248, v248
	v_rcp_f32_e32 v249, v249
	v_rcp_f32_e32 v250, v250
	v_rcp_f32_e32 v251, v251
	v_rcp_f32_e32 v252, v252
	v_rcp_f32_e32 v253, v253
	v_rcp_f32_e32 v254, v254
	v_rcp_f32_e32 v255, v255
	s_nop 0
	v_pk_mul_f32 v[158:159], v[248:249], v[158:159]
	v_pk_mul_f32 v[160:161], v[250:251], v[160:161]
	v_pk_mul_f32 v[162:163], v[252:253], v[162:163]
	v_pk_mul_f32 v[232:233], v[254:255], v[232:233]
	v_pk_mul_f32 v[118:119], v[118:119], v[158:159]
	v_pk_mul_f32 v[120:121], v[120:121], v[160:161]
	v_pk_mul_f32 v[110:111], v[110:111], v[162:163]
	v_pk_mul_f32 v[112:113], v[112:113], v[232:233]
	s_waitcnt vmcnt(14)
	v_lshlrev_b32_e32 v248, 16, v212
	v_and_b32_e32 v249, 0xffff0000, v212
	v_lshlrev_b32_e32 v250, 16, v213
	v_and_b32_e32 v251, 0xffff0000, v213
	v_lshlrev_b32_e32 v252, 16, v214
	v_and_b32_e32 v253, 0xffff0000, v214
	v_lshlrev_b32_e32 v254, 16, v215
	v_and_b32_e32 v255, 0xffff0000, v215
	v_lshlrev_b32_e32 v158, 16, v208
	v_and_b32_e32 v159, 0xffff0000, v208
	v_lshlrev_b32_e32 v160, 16, v209
	v_and_b32_e32 v161, 0xffff0000, v209
	v_lshlrev_b32_e32 v162, 16, v210
	v_and_b32_e32 v163, 0xffff0000, v210
	v_lshlrev_b32_e32 v232, 16, v211
	v_and_b32_e32 v233, 0xffff0000, v211
	v_add_u32_e32 v4, 0x48000, v3
	global_load_dwordx4 v[208:211], v4, s[8:9]
	global_load_dwordx4 v[212:215], v4, s[10:11]
	v_max_f32_e32 v248, 0xda24260, v248
	v_max_f32_e32 v249, 0xda24260, v249
	v_max_f32_e32 v250, 0xda24260, v250
	v_max_f32_e32 v251, 0xda24260, v251
	v_max_f32_e32 v252, 0xda24260, v252
	v_max_f32_e32 v253, 0xda24260, v253
	v_max_f32_e32 v254, 0xda24260, v254
	v_max_f32_e32 v255, 0xda24260, v255
	v_rcp_f32_e32 v248, v248
	v_rcp_f32_e32 v249, v249
	v_rcp_f32_e32 v250, v250
	v_rcp_f32_e32 v251, v251
	v_rcp_f32_e32 v252, v252
	v_rcp_f32_e32 v253, v253
	v_rcp_f32_e32 v254, v254
	v_rcp_f32_e32 v255, v255
	s_nop 0
	v_pk_mul_f32 v[158:159], v[248:249], v[158:159]
	v_pk_mul_f32 v[160:161], v[250:251], v[160:161]
	v_pk_mul_f32 v[162:163], v[252:253], v[162:163]
	v_pk_mul_f32 v[232:233], v[254:255], v[232:233]
	v_pk_mul_f32 v[122:123], v[122:123], v[158:159]
	v_pk_mul_f32 v[124:125], v[124:125], v[160:161]
	v_pk_mul_f32 v[114:115], v[114:115], v[162:163]
	v_pk_mul_f32 v[116:117], v[116:117], v[232:233]
	s_waitcnt vmcnt(14)
	v_lshlrev_b32_e32 v248, 16, v220
	v_and_b32_e32 v249, 0xffff0000, v220
	v_lshlrev_b32_e32 v250, 16, v221
	v_and_b32_e32 v251, 0xffff0000, v221
	v_lshlrev_b32_e32 v252, 16, v222
	v_and_b32_e32 v253, 0xffff0000, v222
	v_lshlrev_b32_e32 v254, 16, v223
	v_and_b32_e32 v255, 0xffff0000, v223
	v_lshlrev_b32_e32 v158, 16, v216
	v_and_b32_e32 v159, 0xffff0000, v216
	v_lshlrev_b32_e32 v160, 16, v217
	v_and_b32_e32 v161, 0xffff0000, v217
	v_lshlrev_b32_e32 v162, 16, v218
	v_and_b32_e32 v163, 0xffff0000, v218
	v_lshlrev_b32_e32 v232, 16, v219
	v_and_b32_e32 v233, 0xffff0000, v219
	global_load_dwordx4 v[216:219], v4, s[8:9] offset:256
	global_load_dwordx4 v[220:223], v4, s[10:11] offset:256
	v_max_f32_e32 v248, 0xda24260, v248
	v_max_f32_e32 v249, 0xda24260, v249
	v_max_f32_e32 v250, 0xda24260, v250
	v_max_f32_e32 v251, 0xda24260, v251
	v_max_f32_e32 v252, 0xda24260, v252
	v_max_f32_e32 v253, 0xda24260, v253
	v_max_f32_e32 v254, 0xda24260, v254
	v_max_f32_e32 v255, 0xda24260, v255
	v_rcp_f32_e32 v248, v248
	v_rcp_f32_e32 v249, v249
	v_rcp_f32_e32 v250, v250
	v_rcp_f32_e32 v251, v251
	v_rcp_f32_e32 v252, v252
	v_rcp_f32_e32 v253, v253
	v_rcp_f32_e32 v254, v254
	v_rcp_f32_e32 v255, v255
	s_nop 0
	v_pk_mul_f32 v[158:159], v[248:249], v[158:159]
	v_pk_mul_f32 v[160:161], v[250:251], v[160:161]
	v_pk_mul_f32 v[162:163], v[252:253], v[162:163]
	v_pk_mul_f32 v[232:233], v[254:255], v[232:233]
	v_pk_mul_f32 v[106:107], v[106:107], v[158:159]
	v_pk_mul_f32 v[108:109], v[108:109], v[160:161]
	v_pk_mul_f32 v[102:103], v[102:103], v[162:163]
	v_pk_mul_f32 v[104:105], v[104:105], v[232:233]
	s_waitcnt vmcnt(14)
	v_lshlrev_b32_e32 v248, 16, v228
	v_and_b32_e32 v249, 0xffff0000, v228
	v_lshlrev_b32_e32 v250, 16, v229
	v_and_b32_e32 v251, 0xffff0000, v229
	v_lshlrev_b32_e32 v252, 16, v230
	v_and_b32_e32 v253, 0xffff0000, v230
	v_lshlrev_b32_e32 v254, 16, v231
	v_and_b32_e32 v255, 0xffff0000, v231
	v_lshlrev_b32_e32 v158, 16, v224
	v_and_b32_e32 v159, 0xffff0000, v224
	v_lshlrev_b32_e32 v160, 16, v225
	v_and_b32_e32 v161, 0xffff0000, v225
	v_lshlrev_b32_e32 v162, 16, v226
	v_and_b32_e32 v163, 0xffff0000, v226
	v_lshlrev_b32_e32 v232, 16, v227
	v_and_b32_e32 v233, 0xffff0000, v227
	v_add_u32_e32 v4, 0x50000, v3
	global_load_dwordx4 v[224:227], v4, s[8:9]
	global_load_dwordx4 v[228:231], v4, s[10:11]
	v_max_f32_e32 v248, 0xda24260, v248
	v_max_f32_e32 v249, 0xda24260, v249
	v_max_f32_e32 v250, 0xda24260, v250
	v_max_f32_e32 v251, 0xda24260, v251
	v_max_f32_e32 v252, 0xda24260, v252
	v_max_f32_e32 v253, 0xda24260, v253
	v_max_f32_e32 v254, 0xda24260, v254
	v_max_f32_e32 v255, 0xda24260, v255
	v_rcp_f32_e32 v248, v248
	v_rcp_f32_e32 v249, v249
	v_rcp_f32_e32 v250, v250
	v_rcp_f32_e32 v251, v251
	v_rcp_f32_e32 v252, v252
	v_rcp_f32_e32 v253, v253
	v_rcp_f32_e32 v254, v254
	v_rcp_f32_e32 v255, v255
	s_nop 0
	v_pk_mul_f32 v[158:159], v[248:249], v[158:159]
	v_pk_mul_f32 v[160:161], v[250:251], v[160:161]
	v_pk_mul_f32 v[162:163], v[252:253], v[162:163]
	v_pk_mul_f32 v[232:233], v[254:255], v[232:233]
	v_pk_mul_f32 v[98:99], v[98:99], v[158:159]
	v_pk_mul_f32 v[100:101], v[100:101], v[160:161]
	v_pk_mul_f32 v[94:95], v[94:95], v[162:163]
	v_pk_mul_f32 v[96:97], v[96:97], v[232:233]
	s_waitcnt vmcnt(14)
	v_lshlrev_b32_e32 v248, 16, v138
	v_and_b32_e32 v249, 0xffff0000, v138
	v_lshlrev_b32_e32 v250, 16, v139
	v_and_b32_e32 v251, 0xffff0000, v139
	v_lshlrev_b32_e32 v252, 16, v140
	v_and_b32_e32 v253, 0xffff0000, v140
	v_lshlrev_b32_e32 v254, 16, v141
	v_and_b32_e32 v255, 0xffff0000, v141
	v_lshlrev_b32_e32 v158, 16, v134
	v_and_b32_e32 v159, 0xffff0000, v134
	v_lshlrev_b32_e32 v160, 16, v135
	v_and_b32_e32 v161, 0xffff0000, v135
	v_lshlrev_b32_e32 v162, 16, v136
	v_and_b32_e32 v163, 0xffff0000, v136
	v_lshlrev_b32_e32 v232, 16, v137
	v_and_b32_e32 v233, 0xffff0000, v137
	global_load_dwordx4 v[134:137], v4, s[8:9] offset:256
	global_load_dwordx4 v[138:141], v4, s[10:11] offset:256
	v_max_f32_e32 v248, 0xda24260, v248
	v_max_f32_e32 v249, 0xda24260, v249
	v_max_f32_e32 v250, 0xda24260, v250
	v_max_f32_e32 v251, 0xda24260, v251
	v_max_f32_e32 v252, 0xda24260, v252
	v_max_f32_e32 v253, 0xda24260, v253
	v_max_f32_e32 v254, 0xda24260, v254
	v_max_f32_e32 v255, 0xda24260, v255
	v_rcp_f32_e32 v248, v248
	v_rcp_f32_e32 v249, v249
	v_rcp_f32_e32 v250, v250
	v_rcp_f32_e32 v251, v251
	v_rcp_f32_e32 v252, v252
	v_rcp_f32_e32 v253, v253
	v_rcp_f32_e32 v254, v254
	v_rcp_f32_e32 v255, v255
	s_nop 0
	v_pk_mul_f32 v[158:159], v[248:249], v[158:159]
	v_pk_mul_f32 v[160:161], v[250:251], v[160:161]
	v_pk_mul_f32 v[162:163], v[252:253], v[162:163]
	v_pk_mul_f32 v[232:233], v[254:255], v[232:233]
	v_pk_mul_f32 v[90:91], v[90:91], v[158:159]
	v_pk_mul_f32 v[92:93], v[92:93], v[160:161]
	v_pk_mul_f32 v[86:87], v[86:87], v[162:163]
	v_pk_mul_f32 v[88:89], v[88:89], v[232:233]
	s_waitcnt vmcnt(14)
	v_lshlrev_b32_e32 v248, 16, v146
	v_and_b32_e32 v249, 0xffff0000, v146
	v_lshlrev_b32_e32 v250, 16, v147
	v_and_b32_e32 v251, 0xffff0000, v147
	v_lshlrev_b32_e32 v252, 16, v148
	v_and_b32_e32 v253, 0xffff0000, v148
	v_lshlrev_b32_e32 v254, 16, v149
	v_and_b32_e32 v255, 0xffff0000, v149
	v_lshlrev_b32_e32 v158, 16, v142
	v_and_b32_e32 v159, 0xffff0000, v142
	v_lshlrev_b32_e32 v160, 16, v143
	v_and_b32_e32 v161, 0xffff0000, v143
	v_lshlrev_b32_e32 v162, 16, v144
	v_and_b32_e32 v163, 0xffff0000, v144
	v_lshlrev_b32_e32 v232, 16, v145
	v_and_b32_e32 v233, 0xffff0000, v145
	v_add_u32_e32 v4, 0x58000, v3
	global_load_dwordx4 v[142:145], v4, s[8:9]
	global_load_dwordx4 v[146:149], v4, s[10:11]
	v_max_f32_e32 v248, 0xda24260, v248
	v_max_f32_e32 v249, 0xda24260, v249
	v_max_f32_e32 v250, 0xda24260, v250
	v_max_f32_e32 v251, 0xda24260, v251
	v_max_f32_e32 v252, 0xda24260, v252
	v_max_f32_e32 v253, 0xda24260, v253
	v_max_f32_e32 v254, 0xda24260, v254
	v_max_f32_e32 v255, 0xda24260, v255
	v_rcp_f32_e32 v248, v248
	v_rcp_f32_e32 v249, v249
	v_rcp_f32_e32 v250, v250
	v_rcp_f32_e32 v251, v251
	v_rcp_f32_e32 v252, v252
	v_rcp_f32_e32 v253, v253
	v_rcp_f32_e32 v254, v254
	v_rcp_f32_e32 v255, v255
	s_nop 0
	v_pk_mul_f32 v[158:159], v[248:249], v[158:159]
	v_pk_mul_f32 v[160:161], v[250:251], v[160:161]
	v_pk_mul_f32 v[162:163], v[252:253], v[162:163]
	v_pk_mul_f32 v[232:233], v[254:255], v[232:233]
	v_pk_mul_f32 v[82:83], v[82:83], v[158:159]
	v_pk_mul_f32 v[84:85], v[84:85], v[160:161]
	v_pk_mul_f32 v[78:79], v[78:79], v[162:163]
	v_pk_mul_f32 v[80:81], v[80:81], v[232:233]
	s_waitcnt vmcnt(14)
	v_lshlrev_b32_e32 v248, 16, v154
	v_and_b32_e32 v249, 0xffff0000, v154
	v_lshlrev_b32_e32 v250, 16, v155
	v_and_b32_e32 v251, 0xffff0000, v155
	v_lshlrev_b32_e32 v252, 16, v156
	v_and_b32_e32 v253, 0xffff0000, v156
	v_lshlrev_b32_e32 v254, 16, v157
	v_and_b32_e32 v255, 0xffff0000, v157
	v_lshlrev_b32_e32 v158, 16, v150
	v_and_b32_e32 v159, 0xffff0000, v150
	v_lshlrev_b32_e32 v160, 16, v151
	v_and_b32_e32 v161, 0xffff0000, v151
	v_lshlrev_b32_e32 v162, 16, v152
	v_and_b32_e32 v163, 0xffff0000, v152
	v_lshlrev_b32_e32 v232, 16, v153
	v_and_b32_e32 v233, 0xffff0000, v153
	global_load_dwordx4 v[150:153], v4, s[8:9] offset:256
	global_load_dwordx4 v[154:157], v4, s[10:11] offset:256
	v_max_f32_e32 v248, 0xda24260, v248
	v_max_f32_e32 v249, 0xda24260, v249
	v_max_f32_e32 v250, 0xda24260, v250
	v_max_f32_e32 v251, 0xda24260, v251
	v_max_f32_e32 v252, 0xda24260, v252
	v_max_f32_e32 v253, 0xda24260, v253
	v_max_f32_e32 v254, 0xda24260, v254
	v_max_f32_e32 v255, 0xda24260, v255
	v_rcp_f32_e32 v248, v248
	v_rcp_f32_e32 v249, v249
	v_rcp_f32_e32 v250, v250
	v_rcp_f32_e32 v251, v251
	v_rcp_f32_e32 v252, v252
	v_rcp_f32_e32 v253, v253
	v_rcp_f32_e32 v254, v254
	v_rcp_f32_e32 v255, v255
	s_nop 0
	v_pk_mul_f32 v[158:159], v[248:249], v[158:159]
	v_pk_mul_f32 v[160:161], v[250:251], v[160:161]
	v_pk_mul_f32 v[162:163], v[252:253], v[162:163]
	v_pk_mul_f32 v[232:233], v[254:255], v[232:233]
	v_pk_mul_f32 v[74:75], v[74:75], v[158:159]
	v_pk_mul_f32 v[76:77], v[76:77], v[160:161]
	v_pk_mul_f32 v[70:71], v[70:71], v[162:163]
	v_pk_mul_f32 v[72:73], v[72:73], v[232:233]
	s_waitcnt vmcnt(14)
	v_lshlrev_b32_e32 v248, 16, v196
	v_and_b32_e32 v249, 0xffff0000, v196
	v_lshlrev_b32_e32 v250, 16, v197
	v_and_b32_e32 v251, 0xffff0000, v197
	v_lshlrev_b32_e32 v252, 16, v198
	v_and_b32_e32 v253, 0xffff0000, v198
	v_lshlrev_b32_e32 v254, 16, v199
	v_and_b32_e32 v255, 0xffff0000, v199
	v_lshlrev_b32_e32 v158, 16, v192
	v_and_b32_e32 v159, 0xffff0000, v192
	v_lshlrev_b32_e32 v160, 16, v193
	v_and_b32_e32 v161, 0xffff0000, v193
	v_lshlrev_b32_e32 v162, 16, v194
	v_and_b32_e32 v163, 0xffff0000, v194
	v_lshlrev_b32_e32 v232, 16, v195
	v_and_b32_e32 v233, 0xffff0000, v195
	v_max_f32_e32 v248, 0xda24260, v248
	v_max_f32_e32 v249, 0xda24260, v249
	v_max_f32_e32 v250, 0xda24260, v250
	v_max_f32_e32 v251, 0xda24260, v251
	v_max_f32_e32 v252, 0xda24260, v252
	v_max_f32_e32 v253, 0xda24260, v253
	v_max_f32_e32 v254, 0xda24260, v254
	v_max_f32_e32 v255, 0xda24260, v255
	v_rcp_f32_e32 v248, v248
	v_rcp_f32_e32 v249, v249
	v_rcp_f32_e32 v250, v250
	v_rcp_f32_e32 v251, v251
	v_rcp_f32_e32 v252, v252
	v_rcp_f32_e32 v253, v253
	v_rcp_f32_e32 v254, v254
	v_rcp_f32_e32 v255, v255
	s_nop 0
	v_pk_mul_f32 v[158:159], v[248:249], v[158:159]
	v_pk_mul_f32 v[160:161], v[250:251], v[160:161]
	v_pk_mul_f32 v[162:163], v[252:253], v[162:163]
	v_pk_mul_f32 v[232:233], v[254:255], v[232:233]
	v_pk_mul_f32 v[66:67], v[66:67], v[158:159]
	v_pk_mul_f32 v[68:69], v[68:69], v[160:161]
	v_pk_mul_f32 v[62:63], v[62:63], v[162:163]
	v_pk_mul_f32 v[64:65], v[64:65], v[232:233]
	s_waitcnt vmcnt(12)
	v_lshlrev_b32_e32 v248, 16, v204
	v_and_b32_e32 v249, 0xffff0000, v204
	v_lshlrev_b32_e32 v250, 16, v205
	v_and_b32_e32 v251, 0xffff0000, v205
	v_lshlrev_b32_e32 v252, 16, v206
	v_and_b32_e32 v253, 0xffff0000, v206
	v_lshlrev_b32_e32 v254, 16, v207
	v_and_b32_e32 v255, 0xffff0000, v207
	v_lshlrev_b32_e32 v158, 16, v200
	v_and_b32_e32 v159, 0xffff0000, v200
	v_lshlrev_b32_e32 v160, 16, v201
	v_and_b32_e32 v161, 0xffff0000, v201
	v_lshlrev_b32_e32 v162, 16, v202
	v_and_b32_e32 v163, 0xffff0000, v202
	v_lshlrev_b32_e32 v232, 16, v203
	v_and_b32_e32 v233, 0xffff0000, v203
	v_max_f32_e32 v248, 0xda24260, v248
	v_max_f32_e32 v249, 0xda24260, v249
	v_max_f32_e32 v250, 0xda24260, v250
	v_max_f32_e32 v251, 0xda24260, v251
	v_max_f32_e32 v252, 0xda24260, v252
	v_max_f32_e32 v253, 0xda24260, v253
	v_max_f32_e32 v254, 0xda24260, v254
	v_max_f32_e32 v255, 0xda24260, v255
	v_rcp_f32_e32 v248, v248
	v_rcp_f32_e32 v249, v249
	v_rcp_f32_e32 v250, v250
	v_rcp_f32_e32 v251, v251
	v_rcp_f32_e32 v252, v252
	v_rcp_f32_e32 v253, v253
	v_rcp_f32_e32 v254, v254
	v_rcp_f32_e32 v255, v255
	s_nop 0
	v_pk_mul_f32 v[158:159], v[248:249], v[158:159]
	v_pk_mul_f32 v[160:161], v[250:251], v[160:161]
	v_pk_mul_f32 v[162:163], v[252:253], v[162:163]
	v_pk_mul_f32 v[232:233], v[254:255], v[232:233]
	v_pk_mul_f32 v[58:59], v[58:59], v[158:159]
	v_pk_mul_f32 v[60:61], v[60:61], v[160:161]
	v_pk_mul_f32 v[54:55], v[54:55], v[162:163]
	v_pk_mul_f32 v[56:57], v[56:57], v[232:233]
	s_waitcnt vmcnt(10)
	v_lshlrev_b32_e32 v248, 16, v212
	v_and_b32_e32 v249, 0xffff0000, v212
	v_lshlrev_b32_e32 v250, 16, v213
	v_and_b32_e32 v251, 0xffff0000, v213
	v_lshlrev_b32_e32 v252, 16, v214
	v_and_b32_e32 v253, 0xffff0000, v214
	v_lshlrev_b32_e32 v254, 16, v215
	v_and_b32_e32 v255, 0xffff0000, v215
	v_lshlrev_b32_e32 v158, 16, v208
	v_and_b32_e32 v159, 0xffff0000, v208
	v_lshlrev_b32_e32 v160, 16, v209
	v_and_b32_e32 v161, 0xffff0000, v209
	v_lshlrev_b32_e32 v162, 16, v210
	v_and_b32_e32 v163, 0xffff0000, v210
	v_lshlrev_b32_e32 v232, 16, v211
	v_and_b32_e32 v233, 0xffff0000, v211
	v_max_f32_e32 v248, 0xda24260, v248
	v_max_f32_e32 v249, 0xda24260, v249
	v_max_f32_e32 v250, 0xda24260, v250
	v_max_f32_e32 v251, 0xda24260, v251
	v_max_f32_e32 v252, 0xda24260, v252
	v_max_f32_e32 v253, 0xda24260, v253
	v_max_f32_e32 v254, 0xda24260, v254
	v_max_f32_e32 v255, 0xda24260, v255
	v_rcp_f32_e32 v248, v248
	v_rcp_f32_e32 v249, v249
	v_rcp_f32_e32 v250, v250
	v_rcp_f32_e32 v251, v251
	v_rcp_f32_e32 v252, v252
	v_rcp_f32_e32 v253, v253
	v_rcp_f32_e32 v254, v254
	v_rcp_f32_e32 v255, v255
	s_nop 0
	v_pk_mul_f32 v[158:159], v[248:249], v[158:159]
	v_pk_mul_f32 v[160:161], v[250:251], v[160:161]
	v_pk_mul_f32 v[162:163], v[252:253], v[162:163]
	v_pk_mul_f32 v[232:233], v[254:255], v[232:233]
	v_pk_mul_f32 v[50:51], v[50:51], v[158:159]
	v_pk_mul_f32 v[52:53], v[52:53], v[160:161]
	v_pk_mul_f32 v[46:47], v[46:47], v[162:163]
	v_pk_mul_f32 v[48:49], v[48:49], v[232:233]
	s_waitcnt vmcnt(8)
	v_lshlrev_b32_e32 v248, 16, v220
	v_and_b32_e32 v249, 0xffff0000, v220
	v_lshlrev_b32_e32 v250, 16, v221
	v_and_b32_e32 v251, 0xffff0000, v221
	v_lshlrev_b32_e32 v252, 16, v222
	v_and_b32_e32 v253, 0xffff0000, v222
	v_lshlrev_b32_e32 v254, 16, v223
	v_and_b32_e32 v255, 0xffff0000, v223
	v_lshlrev_b32_e32 v158, 16, v216
	v_and_b32_e32 v159, 0xffff0000, v216
	v_lshlrev_b32_e32 v160, 16, v217
	v_and_b32_e32 v161, 0xffff0000, v217
	v_lshlrev_b32_e32 v162, 16, v218
	v_and_b32_e32 v163, 0xffff0000, v218
	v_lshlrev_b32_e32 v232, 16, v219
	v_and_b32_e32 v233, 0xffff0000, v219
	v_max_f32_e32 v248, 0xda24260, v248
	v_max_f32_e32 v249, 0xda24260, v249
	v_max_f32_e32 v250, 0xda24260, v250
	v_max_f32_e32 v251, 0xda24260, v251
	v_max_f32_e32 v252, 0xda24260, v252
	v_max_f32_e32 v253, 0xda24260, v253
	v_max_f32_e32 v254, 0xda24260, v254
	v_max_f32_e32 v255, 0xda24260, v255
	v_rcp_f32_e32 v248, v248
	v_rcp_f32_e32 v249, v249
	v_rcp_f32_e32 v250, v250
	v_rcp_f32_e32 v251, v251
	v_rcp_f32_e32 v252, v252
	v_rcp_f32_e32 v253, v253
	v_rcp_f32_e32 v254, v254
	v_rcp_f32_e32 v255, v255
	s_nop 0
	v_pk_mul_f32 v[158:159], v[248:249], v[158:159]
	v_pk_mul_f32 v[160:161], v[250:251], v[160:161]
	v_pk_mul_f32 v[162:163], v[252:253], v[162:163]
	v_pk_mul_f32 v[232:233], v[254:255], v[232:233]
	v_pk_mul_f32 v[42:43], v[42:43], v[158:159]
	v_pk_mul_f32 v[44:45], v[44:45], v[160:161]
	v_pk_mul_f32 v[38:39], v[38:39], v[162:163]
	v_pk_mul_f32 v[40:41], v[40:41], v[232:233]
	s_waitcnt vmcnt(6)
	v_lshlrev_b32_e32 v248, 16, v228
	v_and_b32_e32 v249, 0xffff0000, v228
	v_lshlrev_b32_e32 v250, 16, v229
	v_and_b32_e32 v251, 0xffff0000, v229
	v_lshlrev_b32_e32 v252, 16, v230
	v_and_b32_e32 v253, 0xffff0000, v230
	v_lshlrev_b32_e32 v254, 16, v231
	v_and_b32_e32 v255, 0xffff0000, v231
	v_lshlrev_b32_e32 v158, 16, v224
	v_and_b32_e32 v159, 0xffff0000, v224
	v_lshlrev_b32_e32 v160, 16, v225
	v_and_b32_e32 v161, 0xffff0000, v225
	v_lshlrev_b32_e32 v162, 16, v226
	v_and_b32_e32 v163, 0xffff0000, v226
	v_lshlrev_b32_e32 v232, 16, v227
	v_and_b32_e32 v233, 0xffff0000, v227
	v_max_f32_e32 v248, 0xda24260, v248
	v_max_f32_e32 v249, 0xda24260, v249
	v_max_f32_e32 v250, 0xda24260, v250
	v_max_f32_e32 v251, 0xda24260, v251
	v_max_f32_e32 v252, 0xda24260, v252
	v_max_f32_e32 v253, 0xda24260, v253
	v_max_f32_e32 v254, 0xda24260, v254
	v_max_f32_e32 v255, 0xda24260, v255
	v_rcp_f32_e32 v248, v248
	v_rcp_f32_e32 v249, v249
	v_rcp_f32_e32 v250, v250
	v_rcp_f32_e32 v251, v251
	v_rcp_f32_e32 v252, v252
	v_rcp_f32_e32 v253, v253
	v_rcp_f32_e32 v254, v254
	v_rcp_f32_e32 v255, v255
	s_nop 0
	v_pk_mul_f32 v[158:159], v[248:249], v[158:159]
	v_pk_mul_f32 v[160:161], v[250:251], v[160:161]
	v_pk_mul_f32 v[162:163], v[252:253], v[162:163]
	v_pk_mul_f32 v[232:233], v[254:255], v[232:233]
	v_pk_mul_f32 v[34:35], v[34:35], v[158:159]
	v_pk_mul_f32 v[36:37], v[36:37], v[160:161]
	v_pk_mul_f32 v[30:31], v[30:31], v[162:163]
	v_pk_mul_f32 v[32:33], v[32:33], v[232:233]
	s_waitcnt vmcnt(4)
	v_lshlrev_b32_e32 v248, 16, v138
	v_and_b32_e32 v249, 0xffff0000, v138
	v_lshlrev_b32_e32 v250, 16, v139
	v_and_b32_e32 v251, 0xffff0000, v139
	v_lshlrev_b32_e32 v252, 16, v140
	v_and_b32_e32 v253, 0xffff0000, v140
	v_lshlrev_b32_e32 v254, 16, v141
	v_and_b32_e32 v255, 0xffff0000, v141
	v_lshlrev_b32_e32 v158, 16, v134
	v_and_b32_e32 v159, 0xffff0000, v134
	v_lshlrev_b32_e32 v160, 16, v135
	v_and_b32_e32 v161, 0xffff0000, v135
	v_lshlrev_b32_e32 v162, 16, v136
	v_and_b32_e32 v163, 0xffff0000, v136
	v_lshlrev_b32_e32 v232, 16, v137
	v_and_b32_e32 v233, 0xffff0000, v137
	v_max_f32_e32 v248, 0xda24260, v248
	v_max_f32_e32 v249, 0xda24260, v249
	v_max_f32_e32 v250, 0xda24260, v250
	v_max_f32_e32 v251, 0xda24260, v251
	v_max_f32_e32 v252, 0xda24260, v252
	v_max_f32_e32 v253, 0xda24260, v253
	v_max_f32_e32 v254, 0xda24260, v254
	v_max_f32_e32 v255, 0xda24260, v255
	v_rcp_f32_e32 v248, v248
	v_rcp_f32_e32 v249, v249
	v_rcp_f32_e32 v250, v250
	v_rcp_f32_e32 v251, v251
	v_rcp_f32_e32 v252, v252
	v_rcp_f32_e32 v253, v253
	v_rcp_f32_e32 v254, v254
	v_rcp_f32_e32 v255, v255
	s_nop 0
	v_pk_mul_f32 v[158:159], v[248:249], v[158:159]
	v_pk_mul_f32 v[160:161], v[250:251], v[160:161]
	v_pk_mul_f32 v[162:163], v[252:253], v[162:163]
	v_pk_mul_f32 v[232:233], v[254:255], v[232:233]
	v_pk_mul_f32 v[26:27], v[26:27], v[158:159]
	v_pk_mul_f32 v[28:29], v[28:29], v[160:161]
	v_pk_mul_f32 v[22:23], v[22:23], v[162:163]
	v_pk_mul_f32 v[24:25], v[24:25], v[232:233]
	s_waitcnt vmcnt(2)
	v_lshlrev_b32_e32 v248, 16, v146
	v_and_b32_e32 v249, 0xffff0000, v146
	v_lshlrev_b32_e32 v250, 16, v147
	v_and_b32_e32 v251, 0xffff0000, v147
	v_lshlrev_b32_e32 v252, 16, v148
	v_and_b32_e32 v253, 0xffff0000, v148
	v_lshlrev_b32_e32 v254, 16, v149
	v_and_b32_e32 v255, 0xffff0000, v149
	v_lshlrev_b32_e32 v158, 16, v142
	v_and_b32_e32 v159, 0xffff0000, v142
	v_lshlrev_b32_e32 v160, 16, v143
	v_and_b32_e32 v161, 0xffff0000, v143
	v_lshlrev_b32_e32 v162, 16, v144
	v_and_b32_e32 v163, 0xffff0000, v144
	v_lshlrev_b32_e32 v232, 16, v145
	v_and_b32_e32 v233, 0xffff0000, v145
	v_max_f32_e32 v248, 0xda24260, v248
	v_max_f32_e32 v249, 0xda24260, v249
	v_max_f32_e32 v250, 0xda24260, v250
	v_max_f32_e32 v251, 0xda24260, v251
	v_max_f32_e32 v252, 0xda24260, v252
	v_max_f32_e32 v253, 0xda24260, v253
	v_max_f32_e32 v254, 0xda24260, v254
	v_max_f32_e32 v255, 0xda24260, v255
	v_rcp_f32_e32 v248, v248
	v_rcp_f32_e32 v249, v249
	v_rcp_f32_e32 v250, v250
	v_rcp_f32_e32 v251, v251
	v_rcp_f32_e32 v252, v252
	v_rcp_f32_e32 v253, v253
	v_rcp_f32_e32 v254, v254
	v_rcp_f32_e32 v255, v255
	s_nop 0
	v_pk_mul_f32 v[158:159], v[248:249], v[158:159]
	v_pk_mul_f32 v[160:161], v[250:251], v[160:161]
	v_pk_mul_f32 v[162:163], v[252:253], v[162:163]
	v_pk_mul_f32 v[232:233], v[254:255], v[232:233]
	v_pk_mul_f32 v[18:19], v[18:19], v[158:159]
	v_pk_mul_f32 v[20:21], v[20:21], v[160:161]
	v_pk_mul_f32 v[14:15], v[14:15], v[162:163]
	v_pk_mul_f32 v[16:17], v[16:17], v[232:233]
	s_waitcnt vmcnt(0)
	v_lshlrev_b32_e32 v248, 16, v154
	v_and_b32_e32 v249, 0xffff0000, v154
	v_lshlrev_b32_e32 v250, 16, v155
	v_and_b32_e32 v251, 0xffff0000, v155
	v_lshlrev_b32_e32 v252, 16, v156
	v_and_b32_e32 v253, 0xffff0000, v156
	v_lshlrev_b32_e32 v254, 16, v157
	v_and_b32_e32 v255, 0xffff0000, v157
	v_lshlrev_b32_e32 v158, 16, v150
	v_and_b32_e32 v159, 0xffff0000, v150
	v_lshlrev_b32_e32 v160, 16, v151
	v_and_b32_e32 v161, 0xffff0000, v151
	v_lshlrev_b32_e32 v162, 16, v152
	v_and_b32_e32 v163, 0xffff0000, v152
	v_lshlrev_b32_e32 v232, 16, v153
	v_and_b32_e32 v233, 0xffff0000, v153
	v_max_f32_e32 v248, 0xda24260, v248
	v_max_f32_e32 v249, 0xda24260, v249
	v_max_f32_e32 v250, 0xda24260, v250
	v_max_f32_e32 v251, 0xda24260, v251
	v_max_f32_e32 v252, 0xda24260, v252
	v_max_f32_e32 v253, 0xda24260, v253
	v_max_f32_e32 v254, 0xda24260, v254
	v_max_f32_e32 v255, 0xda24260, v255
	v_rcp_f32_e32 v248, v248
	v_rcp_f32_e32 v249, v249
	v_rcp_f32_e32 v250, v250
	v_rcp_f32_e32 v251, v251
	v_rcp_f32_e32 v252, v252
	v_rcp_f32_e32 v253, v253
	v_rcp_f32_e32 v254, v254
	v_rcp_f32_e32 v255, v255
	s_nop 0
	v_pk_mul_f32 v[158:159], v[248:249], v[158:159]
	v_pk_mul_f32 v[160:161], v[250:251], v[160:161]
	v_pk_mul_f32 v[162:163], v[252:253], v[162:163]
	v_pk_mul_f32 v[232:233], v[254:255], v[232:233]
	v_pk_mul_f32 v[10:11], v[10:11], v[158:159]
	v_pk_mul_f32 v[12:13], v[12:13], v[160:161]
	v_pk_mul_f32 v[6:7], v[6:7], v[162:163]
	v_pk_mul_f32 v[8:9], v[8:9], v[232:233]
	s_branch .LBB0_623
